# v16 combo + attention output rows stored as 4 dwordx4 per lane via permlane32_swap (was 8 dwordx2)
# speedup vs baseline: 1.0145x; 1.0077x over previous
; __device__ __forceinline__ unsigned pk2(float lo, float hi) { return pg8::cvt_pk_bf16(lo, hi); }
; __device__ __forceinline__ void prompt_unit(LAS unsigned char* lds, const Ptrs& P, int qloc0, int qglob0, int kloc0, int kglob0, int h, int qb) {
;     ...
;     l += __shfl_xor(l, 32);
;     const float inv = 1.0f / l;
;     bf16_t* orow = P.ATT + (size_t)(qglob0 + 32 * wid + r32) * 1024 + h * 64;
; #pragma unroll
;     for (int db = 0; db < 2; ++db)
; #pragma unroll
;         for (int g = 0; g < 4; ++g) { u32x2 w; w.x = pk2(o[db][4 * g] * inv, o[db][4 * g + 1] * inv); w.y = pk2(o[db][4 * g + 2] * inv, o[db][4 * g + 3] * inv);
;             *(u32x2*)(orow + 32 * db + 8 * g + 4 * hi) = w; }
.Latt_no_catchup:
	s_waitcnt lgkmcnt(0)
	v_lshlrev_b32_e32 v64, 3, v142
	s_mov_b64 s[66:67], 0
	v_add_f32_e32 v32, v135, v32
	v_div_scale_f32 v33, s[38:39], v32, v32, 1.0
	v_rcp_f32_e32 v34, v33
	s_nop 0
	v_fma_f32 v35, -v33, v34, 1.0
	v_fmac_f32_e32 v34, v35, v34
	v_div_scale_f32 v35, vcc, 1.0, v32, 1.0
	v_mul_f32_e32 v36, v35, v34
	v_fma_f32 v37, -v33, v36, v35
	v_fmac_f32_e32 v36, v37, v34
	v_fma_f32 v33, -v33, v36, v35
	v_div_fmas_f32 v33, v33, v34, v36
	v_div_fixup_f32 v34, v33, v32, 1.0
	v_add_u32_e32 v32, s27, v143
	v_ashrrev_i32_e32 v33, 31, v32
	v_lshlrev_b64 v[32:33], 11, v[32:33]
	v_lshl_add_u64 v[32:33], s[36:37], 0, v[32:33]
	v_lshl_add_u64 v[32:33], v[32:33], 0, v[64:65]
	v_lshl_add_u64 v[32:33], v[32:33], 0, v[64:65]
	v_mul_f32_e32 v0, v0, v34
	v_mul_f32_e32 v1, v1, v34
	v_mul_f32_e32 v2, v2, v34
	v_mul_f32_e32 v3, v3, v34
	v_mul_f32_e32 v4, v4, v34
	v_mul_f32_e32 v5, v5, v34
	v_mul_f32_e32 v6, v6, v34
	v_mul_f32_e32 v7, v7, v34
	v_mul_f32_e32 v8, v8, v34
	v_mul_f32_e32 v9, v9, v34
	v_mul_f32_e32 v10, v10, v34
	v_mul_f32_e32 v11, v11, v34
	v_mul_f32_e32 v12, v12, v34
	v_mul_f32_e32 v13, v13, v34
	v_mul_f32_e32 v14, v14, v34
	v_mul_f32_e32 v15, v15, v34
	v_mul_f32_e32 v16, v16, v34
	v_mul_f32_e32 v17, v17, v34
	v_mul_f32_e32 v18, v18, v34
	v_mul_f32_e32 v19, v19, v34
	v_mul_f32_e32 v20, v20, v34
	v_mul_f32_e32 v21, v21, v34
	v_mul_f32_e32 v22, v22, v34
	v_mul_f32_e32 v23, v23, v34
	v_mul_f32_e32 v24, v24, v34
	v_mul_f32_e32 v25, v25, v34
	v_mul_f32_e32 v26, v26, v34
	v_mul_f32_e32 v27, v27, v34
	v_mul_f32_e32 v28, v28, v34
	v_mul_f32_e32 v29, v29, v34
	v_mul_f32_e32 v30, v30, v34
	v_mul_f32_e32 v31, v31, v34
	v_cvt_pk_bf16_f32 v36, v16, v17
	v_cvt_pk_bf16_f32 v37, v18, v19
	v_cvt_pk_bf16_f32 v38, v20, v21
	v_cvt_pk_bf16_f32 v39, v22, v23
	s_nop 1
	v_permlane32_swap_b32_e32 v36, v38
	v_permlane32_swap_b32_e32 v37, v39
	global_store_dwordx4 v[32:33], v[36:39], off
	v_cvt_pk_bf16_f32 v40, v24, v25
	v_cvt_pk_bf16_f32 v41, v26, v27
	v_cvt_pk_bf16_f32 v42, v28, v29
	v_cvt_pk_bf16_f32 v43, v30, v31
	s_nop 1
	v_permlane32_swap_b32_e32 v40, v42
	v_permlane32_swap_b32_e32 v41, v43
	global_store_dwordx4 v[32:33], v[40:43], off offset:32
	v_cvt_pk_bf16_f32 v44, v0, v1
	v_cvt_pk_bf16_f32 v45, v2, v3
	v_cvt_pk_bf16_f32 v46, v4, v5
	v_cvt_pk_bf16_f32 v47, v6, v7
	s_nop 1
	v_permlane32_swap_b32_e32 v44, v46
	v_permlane32_swap_b32_e32 v45, v47
	global_store_dwordx4 v[32:33], v[44:47], off offset:64
	v_cvt_pk_bf16_f32 v48, v8, v9
	v_cvt_pk_bf16_f32 v49, v10, v11
	v_cvt_pk_bf16_f32 v50, v12, v13
	v_cvt_pk_bf16_f32 v51, v14, v15
	s_nop 1
	v_permlane32_swap_b32_e32 v48, v50
	v_permlane32_swap_b32_e32 v49, v51
	global_store_dwordx4 v[32:33], v[48:51], off offset:96
	s_and_b64 vcc, exec, s[64:65]
	s_cbranch_vccnz .LBB0_1139
